# v26 + FoX unit-prologue de-serialisation: 4 own-block K-fragment loads issued together into distinct quads, scale and cumulative-decay loads hoisted to unit top
# baseline (speedup 1.0000x reference)
.LBB0_223:
	s_and_b32 s10, s9, 7
	s_ashr_i32 s11, s9, 6
	s_ashr_i32 s30, s9, 3
	s_xor_b32 s4, s10, 15
	s_mul_i32 s5, s11, 0x1400000
	v_readlane_b32 s16, v255, 48
	s_mul_hi_i32 s1, s11, 0x1400000
	s_add_u32 s5, s16, s5
	v_readlane_b32 s16, v255, 49
	s_addc_u32 s22, s16, s1
	s_lshl_b32 s1, s30, 6
	s_and_b32 s1, s1, 0x1c0
	s_lshl_b32 s16, s1, 1
	s_add_u32 s84, s5, s16
	s_addc_u32 s85, s22, 0
	s_ashr_i32 s31, s30, 31
	s_lshl_b64 s[28:29], s[30:31], 14
	v_readlane_b32 s1, v255, 50
	s_add_u32 s28, s1, s28
	v_readlane_b32 s1, v255, 51
	s_addc_u32 s29, s1, s29
	s_lshl_b64 s[30:31], s[30:31], 2
	v_readlane_b32 s1, v255, 52
	s_add_u32 s96, s1, s30
	v_readlane_b32 s1, v255, 53
	v_mov_b32_e32 v144, v226
	v_mov_b32_e32 v0, v227
	s_addc_u32 s97, s1, s31
	s_lshl_b32 s1, s4, 8
	v_readlane_b32 s17, v251, 7
	s_add_i32 s82, s1, s17
	v_and_b32_e32 v149, 31, v144
	v_ashrrev_i32_e32 v18, 5, v144
	s_mul_i32 s23, s82, 0x1400
	v_mul_u32_u24_e32 v0, 0xa00, v149
	s_mul_hi_u32 s17, s82, 0x1400
	s_add_u32 s30, s84, s23
	v_lshl_add_u32 v0, v18, 3, v0
	s_addc_u32 s31, s85, s17
	v_add_u32_e32 v2, 16, v0
	v_mov_b32_e32 v3, v1
	s_mov_b32 s83, s37
	v_lshl_add_u64 v[20:21], v[0:1], 1, s[30:31]
	v_lshl_add_u64 v[24:25], v[2:3], 1, s[30:31]
	v_add_u32_e32 v2, 32, v0
	v_add_u32_e32 v0, 48, v0
	v_lshl_add_u64 v[26:27], v[2:3], 1, s[30:31]
	v_lshl_add_u64 v[28:29], v[0:1], 1, s[30:31]
	s_lshl_b64 s[30:31], s[82:83], 2
	v_lshlrev_b32_e32 v146, 2, v18
	s_add_u32 s30, s28, s30
	s_addc_u32 s31, s29, s31
	v_ashrrev_i32_e32 v147, 31, v146
	v_lshl_add_u64 v[14:15], v[146:147], 2, s[30:31]
	global_load_dwordx4 v[140:143], v[20:21], off offset:2048
	global_load_dwordx4 v[136:139], v[24:25], off offset:2048
	global_load_dwordx4 v[132:135], v[26:27], off offset:2048
	global_load_dwordx4 v[128:131], v[28:29], off offset:2048
	global_load_dwordx4 v[2:5], v[14:15], off
	global_load_dwordx4 v[6:9], v[14:15], off offset:32
	global_load_dwordx4 v[10:13], v[14:15], off offset:64
	s_nop 0
	global_load_dwordx4 v[14:17], v[14:15], off offset:96
	s_nop 0
	global_load_dword v42, v1, s[96:97]
	s_add_i32 s30, s1, 0x100
	s_lshr_b32 s30, s30, 6
	v_cmp_gt_i32_e32 vcc, s30, v144
	v_mov_b32_e32 v43, 0x7f800000
	v_lshlrev_b32_e32 v44, 6, v144
	v_ashrrev_i32_e32 v45, 31, v44
	v_lshl_add_u64 v[44:45], v[44:45], 2, s[28:29]
	s_and_saveexec_b64 s[30:31], vcc
	global_load_dword v43, v[44:45], off offset:252
	s_or_b64 exec, exec, s[30:31]
	global_load_dwordx4 v[20:23], v[20:21], off offset:3072
	global_load_dwordx4 v[30:33], v[24:25], off offset:3072
	global_load_dwordx4 v[34:37], v[26:27], off offset:3072
	global_load_dwordx4 v[38:41], v[28:29], off offset:3072
	v_cmp_gt_i32_e64 s[42:43], v146, v149
	v_cmp_lt_i32_e64 s[44:45], v146, v149
	v_cmp_lt_i32_e32 vcc, v219, v213
	s_waitcnt vmcnt(3)
	v_mfma_f32_32x32x16_bf16 v[2:17], v[20:23], v[140:143], v[2:17]
	s_waitcnt vmcnt(2)
	v_mfma_f32_32x32x16_bf16 v[2:17], v[30:33], v[136:139], v[2:17]
	s_waitcnt vmcnt(1)
	v_mfma_f32_32x32x16_bf16 v[2:17], v[34:37], v[132:135], v[2:17]
	s_waitcnt vmcnt(0)
	v_mfma_f32_32x32x16_bf16 v[2:17], v[38:41], v[128:131], v[2:17]
	s_nop 11
	v_max_f32_e32 v0, v2, v2
	v_max_f32_e32 v0, 0xff800000, v0
	v_cndmask_b32_e64 v0, v0, v220, s[42:43]
	v_max_f32_e32 v2, v3, v3
	v_max_f32_e32 v2, v0, v2
	v_cndmask_b32_e64 v0, v0, v2, s[44:45]
	v_or_b32_e32 v2, 2, v146
	v_cmp_gt_i32_e64 s[46:47], v2, v149
	v_max_f32_e32 v2, v4, v4
	v_max_f32_e32 v2, v0, v2
	v_cndmask_b32_e64 v0, v2, v0, s[46:47]
	v_or_b32_e32 v2, 3, v146
	v_cmp_gt_i32_e64 s[48:49], v2, v149
	v_max_f32_e32 v2, v5, v5
	v_max_f32_e32 v2, v0, v2
	v_cndmask_b32_e64 v0, v2, v0, s[48:49]
	v_add_u32_e32 v2, 8, v146
	v_cmp_gt_i32_e64 s[50:51], v2, v149
	v_max_f32_e32 v2, v6, v6
	v_max_f32_e32 v2, v0, v2
	v_cndmask_b32_e64 v0, v2, v0, s[50:51]
	v_add_u32_e32 v2, 9, v146
	v_cmp_gt_i32_e64 s[52:53], v2, v149
	v_max_f32_e32 v2, v0, v0
	v_max_f32_e32 v3, v7, v7
	v_max_f32_e32 v2, v2, v3
	v_cndmask_b32_e64 v0, v2, v0, s[52:53]
	v_add_u32_e32 v2, 10, v146
	v_cmp_gt_i32_e64 s[54:55], v2, v149
	v_max_f32_e32 v2, v0, v0
	v_max_f32_e32 v3, v8, v8
	v_max_f32_e32 v2, v2, v3
	v_cndmask_b32_e64 v0, v2, v0, s[54:55]
	v_add_u32_e32 v2, 11, v146
	v_cmp_gt_i32_e64 s[56:57], v2, v149
	v_max_f32_e32 v2, v0, v0
	v_max_f32_e32 v3, v9, v9
	v_max_f32_e32 v2, v2, v3
	v_cndmask_b32_e64 v0, v2, v0, s[56:57]
	v_add_u32_e32 v2, 16, v146
	v_cmp_gt_i32_e64 s[58:59], v2, v149
	v_max_f32_e32 v2, v0, v0
	v_max_f32_e32 v3, v10, v10
	v_max_f32_e32 v2, v2, v3
	v_cndmask_b32_e64 v0, v2, v0, s[58:59]
	v_add_u32_e32 v2, 17, v146
	v_cmp_gt_i32_e64 s[60:61], v2, v149
	v_max_f32_e32 v2, v0, v0
	v_max_f32_e32 v3, v11, v11
	v_max_f32_e32 v2, v2, v3
	v_cndmask_b32_e64 v0, v2, v0, s[60:61]
	v_add_u32_e32 v2, 18, v146
	v_cmp_gt_i32_e64 s[62:63], v2, v149
	v_max_f32_e32 v2, v0, v0
	v_max_f32_e32 v3, v12, v12
	v_max_f32_e32 v2, v2, v3
	v_cndmask_b32_e64 v0, v2, v0, s[62:63]
	v_add_u32_e32 v2, 19, v146
	v_cmp_gt_i32_e64 s[64:65], v2, v149
	v_max_f32_e32 v2, v0, v0
	v_max_f32_e32 v3, v13, v13
	v_max_f32_e32 v2, v2, v3
	v_cndmask_b32_e64 v0, v2, v0, s[64:65]
	v_add_u32_e32 v2, 24, v146
	v_cmp_gt_i32_e64 s[66:67], v2, v149
	v_max_f32_e32 v2, v0, v0
	v_max_f32_e32 v3, v14, v14
	v_max_f32_e32 v2, v2, v3
	v_cndmask_b32_e64 v0, v2, v0, s[66:67]
	v_add_u32_e32 v2, 25, v146
	v_cmp_gt_i32_e64 s[68:69], v2, v149
	v_max_f32_e32 v2, v0, v0
	v_max_f32_e32 v3, v15, v15
	v_max_f32_e32 v2, v2, v3
	v_cndmask_b32_e64 v0, v2, v0, s[68:69]
	v_add_u32_e32 v2, 26, v146
	v_cmp_gt_i32_e64 s[70:71], v2, v149
	v_max_f32_e32 v2, v0, v0
	v_max_f32_e32 v3, v16, v16
	v_max_f32_e32 v2, v2, v3
	v_cndmask_b32_e64 v0, v2, v0, s[70:71]
	v_add_u32_e32 v2, 27, v146
	v_cmp_gt_i32_e64 s[72:73], v2, v149
	v_max_f32_e32 v2, v0, v0
	v_max_f32_e32 v3, v17, v17
	v_max_f32_e32 v2, v2, v3
	v_cndmask_b32_e64 v0, v2, v0, s[72:73]
	v_cndmask_b32_e32 v2, v211, v219, vcc
	v_lshlrev_b32_e32 v147, 2, v2
	ds_bpermute_b32 v2, v147, v0
	v_max_f32_e32 v0, v0, v0
	v_and_b32_e32 v3, 0xffff0000, v140
	v_mul_f32_e32 v3, v3, v3
	v_cmp_lt_i32_e32 vcc, v250, v213
	s_waitcnt lgkmcnt(0)
	v_max_f32_e32 v2, v2, v2
	v_max_f32_e32 v0, v0, v2
	v_lshlrev_b32_e32 v2, 16, v140
	v_fmac_f32_e32 v3, v2, v2
	v_lshlrev_b32_e32 v2, 16, v141
	v_fmac_f32_e32 v3, v2, v2
	v_and_b32_e32 v2, 0xffff0000, v141
	v_fmac_f32_e32 v3, v2, v2
	v_lshlrev_b32_e32 v2, 16, v142
	v_fmac_f32_e32 v3, v2, v2
	v_and_b32_e32 v2, 0xffff0000, v142
	v_fmac_f32_e32 v3, v2, v2
	v_lshlrev_b32_e32 v2, 16, v143
	v_fmac_f32_e32 v3, v2, v2
	v_and_b32_e32 v2, 0xffff0000, v143
	v_fmac_f32_e32 v3, v2, v2
	v_lshlrev_b32_e32 v2, 16, v136
	v_fmac_f32_e32 v3, v2, v2
	v_and_b32_e32 v2, 0xffff0000, v136
	v_fmac_f32_e32 v3, v2, v2
	v_lshlrev_b32_e32 v2, 16, v137
	v_fmac_f32_e32 v3, v2, v2
	v_and_b32_e32 v2, 0xffff0000, v137
	v_fmac_f32_e32 v3, v2, v2
	v_lshlrev_b32_e32 v2, 16, v138
	v_fmac_f32_e32 v3, v2, v2
	v_and_b32_e32 v2, 0xffff0000, v138
	v_fmac_f32_e32 v3, v2, v2
	v_lshlrev_b32_e32 v2, 16, v139
	v_fmac_f32_e32 v3, v2, v2
	v_and_b32_e32 v2, 0xffff0000, v139
	v_fmac_f32_e32 v3, v2, v2
	v_lshlrev_b32_e32 v2, 16, v132
	v_fmac_f32_e32 v3, v2, v2
	v_and_b32_e32 v2, 0xffff0000, v132
	v_fmac_f32_e32 v3, v2, v2
	v_lshlrev_b32_e32 v2, 16, v133
	v_fmac_f32_e32 v3, v2, v2
	v_and_b32_e32 v2, 0xffff0000, v133
	v_fmac_f32_e32 v3, v2, v2
	v_lshlrev_b32_e32 v2, 16, v134
	v_fmac_f32_e32 v3, v2, v2
	v_and_b32_e32 v2, 0xffff0000, v134
	v_fmac_f32_e32 v3, v2, v2
	v_lshlrev_b32_e32 v2, 16, v135
	v_fmac_f32_e32 v3, v2, v2
	v_and_b32_e32 v2, 0xffff0000, v135
	v_fmac_f32_e32 v3, v2, v2
	v_lshlrev_b32_e32 v2, 16, v128
	v_fmac_f32_e32 v3, v2, v2
	v_and_b32_e32 v2, 0xffff0000, v128
	v_fmac_f32_e32 v3, v2, v2
	v_lshlrev_b32_e32 v2, 16, v129
	v_fmac_f32_e32 v3, v2, v2
	v_and_b32_e32 v2, 0xffff0000, v129
	v_fmac_f32_e32 v3, v2, v2
	v_lshlrev_b32_e32 v2, 16, v130
	v_fmac_f32_e32 v3, v2, v2
	v_and_b32_e32 v2, 0xffff0000, v130
	v_fmac_f32_e32 v3, v2, v2
	v_lshlrev_b32_e32 v2, 16, v131
	v_fmac_f32_e32 v3, v2, v2
	v_and_b32_e32 v2, 0xffff0000, v131
	v_fmac_f32_e32 v3, v2, v2
	v_add_f32_e32 v161, 0xc2200000, v0
	ds_bpermute_b32 v0, v147, v3
	s_waitcnt lgkmcnt(0)
	v_add_f32_e32 v0, v3, v0
	s_waitcnt vmcnt(0)
	v_mul_f32_e32 v0, v42, v0
	v_sqrt_f32_e32 v0, v0
	v_cndmask_b32_e32 v2, v211, v250, vcc
	v_lshlrev_b32_e32 v156, 2, v2
	v_cmp_lt_i32_e32 vcc, v221, v213
	v_fmamk_f32 v0, v0, 0xbf8020c5, v161
	v_add_f32_e32 v0, 0xbc23d70a, v0
	ds_bpermute_b32 v2, v156, v0
	s_waitcnt lgkmcnt(0)
	v_max_f32_e32 v2, v2, v2
	v_min_f32_e32 v0, v0, v2
	v_cndmask_b32_e32 v2, v211, v221, vcc
	v_lshlrev_b32_e32 v157, 2, v2
	ds_bpermute_b32 v2, v157, v0
	v_cmp_lt_i32_e32 vcc, v212, v213
	s_waitcnt lgkmcnt(0)
	v_max_f32_e32 v2, v2, v2
	v_min_f32_e32 v0, v0, v2
	v_cndmask_b32_e32 v2, v211, v212, vcc
	v_lshlrev_b32_e32 v158, 2, v2
	ds_bpermute_b32 v2, v158, v0
	v_cmp_lt_i32_e32 vcc, v210, v213
	s_waitcnt lgkmcnt(0)
	v_max_f32_e32 v2, v2, v2
	v_min_f32_e32 v0, v0, v2
	v_cndmask_b32_e32 v2, v211, v210, vcc
	v_lshlrev_b32_e32 v159, 2, v2
	ds_bpermute_b32 v2, v159, v0
	v_cmp_lt_i32_e32 vcc, v218, v213
	s_waitcnt lgkmcnt(0)
	v_max_f32_e32 v2, v2, v2
	v_min_f32_e32 v0, v0, v2
	v_cndmask_b32_e32 v2, v211, v218, vcc
	v_lshlrev_b32_e32 v160, 2, v2
	ds_bpermute_b32 v2, v160, v0
	v_cmp_eq_u32_e32 vcc, 0, v144
	s_and_saveexec_b64 s[30:31], vcc
	s_cbranch_execz .LBB0_225
	s_waitcnt lgkmcnt(0)
	v_max_f32_e32 v2, v2, v2
	v_max_f32_e32 v0, v0, v0
	v_readlane_b32 s17, v251, 13
	v_min_f32_e32 v0, v0, v2
	s_nop 0
	v_mov_b32_e32 v2, s17
	ds_write_b32 v2, v0
.LBB0_225:
	s_or_b64 exec, exec, s[30:31]
	v_readlane_b32 s17, v254, 36
	s_add_i32 s80, 0, 0x1a000
	s_waitcnt lgkmcnt(0)
	s_barrier
	v_mov_b32_e32 v0, s80
	s_waitcnt lgkmcnt(0)
	v_mov_b32_e32 v2, s17
	v_readlane_b32 s17, v254, 37
	s_addk_i32 s1, 0x100
	s_lshr_b32 s1, s1, 6
	v_mov_b32_e32 v3, s17
	v_readlane_b32 s17, v254, 38
	v_cmp_gt_i32_e32 vcc, s1, v144
	s_nop 0
	v_mov_b32_e32 v4, s17
	v_readlane_b32 s17, v254, 39
	s_nop 1
	v_mov_b32_e32 v5, s17
	v_readlane_b32 s17, v254, 40
	s_nop 1
	v_mov_b32_e32 v7, s17
	v_readlane_b32 s17, v254, 41
	s_nop 1
	v_mov_b32_e32 v8, s17
	v_readlane_b32 s17, v254, 42
	s_nop 1
	v_mov_b32_e32 v9, s17
	ds_read_b32 v0, v0
	ds_read_b32 v6, v2
	ds_read_b32 v3, v3
	ds_read_b32 v4, v4
	ds_read_b32 v5, v5
	ds_read_b32 v7, v7
	ds_read_b32 v8, v8
	ds_read_b32 v9, v9
	v_mov_b32_e32 v2, v43
.LBB0_227:
	s_waitcnt lgkmcnt(6)
	v_max_f32_e32 v6, v6, v6
	v_max_f32_e32 v0, v0, v0
	v_min_f32_e32 v0, v0, v6
	s_waitcnt lgkmcnt(4)
	v_min3_f32 v0, v0, v3, v4
	s_add_u32 s5, s5, s16
	s_waitcnt lgkmcnt(2)
	v_min3_f32 v0, v0, v5, v7
	s_addc_u32 s17, s22, 0
	s_waitcnt lgkmcnt(0)
	v_min3_f32 v3, v0, v8, v9
	s_add_u32 s30, s5, 0x1000
	v_ashrrev_i32_e32 v148, 3, v144
	v_readlane_b32 s5, v251, 12
	s_waitcnt vmcnt(0)
	v_cmp_ge_f32_e32 vcc, v2, v3
	s_addc_u32 s31, s17, 0
	v_add_u32_e32 v0, s5, v148
	s_movk_i32 s5, 0xa00
	v_mul_lo_u32 v0, v0, s5
	s_ff1_i32_b64 s5, vcc
	s_lshl_b32 s4, s4, 2
	s_min_u32 s74, s5, s4
	s_cmp_lg_u64 vcc, 0
	v_xor_b32_e32 v4, v148, v144
	s_cselect_b32 s17, s74, 0
	v_lshlrev_b32_e32 v4, 3, v4
	s_lshl_b32 s38, s17, 6
	s_mul_i32 s40, s17, 0x50000
	v_and_or_b32 v0, v4, 56, v0
	s_add_u32 s4, s84, s40
	s_addc_u32 s5, s85, 0
	v_lshlrev_b64 v[64:65], 1, v[0:1]
	s_waitcnt lgkmcnt(0)
	s_barrier
	v_lshl_add_u64 v[2:3], s[4:5], 0, v[64:65]
	s_mov_b64 s[78:79], 0xc00
	v_lshl_add_u64 v[2:3], v[2:3], 0, s[78:79]
	s_mov_b32 s4, m0
	s_mov_b32 m0, s0
	s_nop 0
	global_load_lds_dwordx4 v[2:3], off
	s_mov_b32 m0, s4
	s_add_u32 s4, s30, s40
	s_addc_u32 s5, s31, 0
	v_lshl_add_u64 v[2:3], s[4:5], 0, v[64:65]
	s_mov_b32 s4, m0
	s_mov_b32 m0, s27
	s_nop 0
	global_load_lds_dwordx4 v[2:3], off
	s_mov_b32 m0, s4
	s_lshl_b32 s36, s17, 8
	s_add_u32 s4, s28, s36
	v_ashrrev_i32_e32 v145, 31, v144
	s_addc_u32 s5, s29, 0
	v_lshlrev_b64 v[6:7], 2, v[144:145]
	v_lshl_add_u64 v[2:3], s[4:5], 0, v[6:7]
	s_add_i32 s26, s0, 0x18000
	s_mov_b32 s4, m0
	s_mov_b32 m0, s26
	s_nop 0
	global_load_lds_dword v[2:3], off
	s_mov_b32 m0, s4
	s_add_i32 s4, s38, 64
	s_add_i32 s22, s40, 0x50000
	s_mul_hi_u32 s39, s4, 0x1400
	s_add_u32 s4, s84, s22
	s_addc_u32 s5, s85, s39
	v_lshl_add_u64 v[4:5], s[4:5], 0, v[64:65]
	v_lshl_add_u64 v[4:5], v[4:5], 0, s[78:79]
	s_add_i32 s23, s0, 0x2000
	s_mov_b32 s4, m0
	s_mov_b32 m0, s23
	s_nop 0
	global_load_lds_dwordx4 v[4:5], off
	s_mov_b32 m0, s4
	s_add_u32 s4, s30, s22
	s_addc_u32 s5, s31, s39
	v_lshl_add_u64 v[4:5], s[4:5], 0, v[64:65]
	s_add_i32 s22, s0, 0xc000
	s_mov_b32 s4, m0
	s_mov_b32 m0, s22
	s_nop 0
	global_load_lds_dwordx4 v[4:5], off
	s_mov_b32 m0, s4
	v_lshl_add_u64 v[4:5], v[2:3], 0, s[24:25]
	s_add_i32 s39, s0, 0x18100
	s_mov_b32 s4, m0
	s_mov_b32 m0, s39
	s_nop 0
	global_load_lds_dword v[4:5], off
	s_mov_b32 m0, s4
	s_addk_i32 s38, 0x80
	s_add_i32 s40, s40, 0xa0000
	s_mul_hi_u32 s75, s38, 0x1400
	s_add_u32 s4, s84, s40
	s_addc_u32 s5, s85, s75
	v_lshl_add_u64 v[4:5], s[4:5], 0, v[64:65]
	v_lshl_add_u64 v[4:5], v[4:5], 0, s[78:79]
	s_add_i32 s38, s0, 0x4000
	s_mov_b32 s4, m0
	s_mov_b32 m0, s38
	s_nop 0
	global_load_lds_dwordx4 v[4:5], off
	s_mov_b32 m0, s4
	s_add_u32 s4, s30, s40
	s_addc_u32 s5, s31, s75
	v_lshl_add_u64 v[4:5], s[4:5], 0, v[64:65]
	s_add_i32 s5, s0, 0x10000
	s_mov_b32 s4, m0
	s_mov_b32 m0, s5
	s_nop 0
	global_load_lds_dwordx4 v[4:5], off
	s_mov_b32 m0, s4
	v_lshl_add_u64 v[2:3], v[2:3], 0, s[86:87]
	s_add_i32 s4, s0, 0x18200
	s_mov_b32 s40, m0
	s_mov_b32 m0, s4
	s_nop 0
	global_load_lds_dword v[2:3], off
	s_mov_b32 m0, s40
	v_lshlrev_b32_e32 v166, 4, v18
	v_readlane_b32 s40, v251, 14
	s_waitcnt vmcnt(3) lgkmcnt(0)
	s_barrier
	v_lshlrev_b32_e32 v167, 7, v149
	v_add_u32_e32 v72, 0, v167
	v_add_u32_e32 v0, s40, v166
	ds_read_b128 v[96:99], v0
	ds_read_b128 v[100:103], v0 offset:32
	ds_read_b128 v[104:107], v0 offset:64
	ds_read_b128 v[108:111], v0 offset:96
	v_bitop3_b32 v0, v18, v144, 7 bitop3:0x78
	v_lshlrev_b32_e32 v168, 4, v0
	v_add_u32_e32 v0, v72, v168
	ds_read_b128 v[2:5], v0
	v_add_u32_e32 v0, 2, v18
	v_bitop3_b32 v0, v0, v144, 7 bitop3:0x78
	v_lshlrev_b32_e32 v171, 4, v0
	v_add_u32_e32 v0, v72, v171
	s_waitcnt lgkmcnt(0)
	v_mfma_f32_32x32x16_bf16 v[96:111], v[2:5], v[140:143], v[96:111]
	ds_read_b128 v[2:5], v0
	v_add_u32_e32 v0, 4, v18
	v_bitop3_b32 v0, v0, v144, 7 bitop3:0x78
	v_lshlrev_b32_e32 v169, 4, v0
	v_add_u32_e32 v0, v72, v169
	v_bfe_u32 v163, v144, 2, 2
	s_lshr_b32 s40, s82, 6
	s_waitcnt lgkmcnt(0)
	v_mfma_f32_32x32x16_bf16 v[96:111], v[2:5], v[136:139], v[96:111]
	ds_read_b128 v[2:5], v0
	v_add_u32_e32 v0, 6, v18
	v_bitop3_b32 v0, v0, v144, 7 bitop3:0x78
	v_lshlrev_b32_e32 v170, 4, v0
	v_add_u32_e32 v0, v72, v170
	v_bfe_u32 v164, v144, 4, 1
	v_and_b32_e32 v165, 3, v144
	s_waitcnt lgkmcnt(0)
	v_mfma_f32_32x32x16_bf16 v[96:111], v[2:5], v[132:135], v[96:111]
	ds_read_b128 v[2:5], v0
	v_or_b32_e32 v162, v146, v163
	s_mov_b32 s83, 0
	s_mov_b64 s[86:87], 0xc00
	v_lshl_add_u64 v[152:153], s[30:31], 0, v[64:65]
	v_lshl_add_u64 v[154:155], s[28:29], 0, v[6:7]
	s_cmp_ge_u32 s17, s40
	s_waitcnt lgkmcnt(0)
	v_mfma_f32_32x32x16_bf16 v[96:111], v[2:5], v[128:131], v[96:111]
	v_lshl_add_u64 v[2:3], s[84:85], 0, v[64:65]
	v_lshl_add_u64 v[150:151], v[2:3], 0, s[78:79]
	s_cbranch_scc1 .LBB0_252
	v_lshlrev_b32_e32 v0, 1, v164
	v_lshrrev_b32_e32 v2, 1, v165
	v_or_b32_e32 v3, v0, v2
	v_bitop3_b32 v0, v0, v162, v2 bitop3:0x36
	v_lshlrev_b32_e32 v4, 3, v144
	v_lshlrev_b32_e32 v76, 4, v0
	v_bitop3_b32 v0, v3, v162, 4 bitop3:0x36
	v_lshl_add_u64 v[2:3], v[154:155], 0, s[36:37]
	s_mov_b64 s[78:79], 0x300
	v_and_b32_e32 v4, 8, v4
	v_lshl_add_u64 v[66:67], v[2:3], 0, s[78:79]
	v_mad_u64_u32 v[2:3], s[78:79], s17, v223, v[152:153]
	s_mov_b64 s[90:91], 0xf0000
	v_add_u32_e32 v4, 0, v4
	v_add_lshl_u32 v5, v146, v163, 7
	v_lshl_add_u64 v[68:69], v[2:3], 0, s[90:91]
	v_mad_u64_u32 v[2:3], s[78:79], s17, v223, v[150:151]
	v_mov_b32_e32 v14, v1
	v_mov_b32_e32 v15, v1
	v_readlane_b32 s77, v251, 13
	v_lshlrev_b32_e32 v77, 4, v0
	v_lshl_add_u32 v78, v162, 7, v4
	v_add3_u32 v79, v5, v4, s21
	v_lshl_add_u64 v[70:71], v[2:3], 0, s[90:91]
	v_mov_b32_e32 v0, v1
	v_mov_b32_e32 v2, v1
	v_mov_b32_e32 v3, v1
	v_mov_b32_e32 v4, v1
	v_mov_b32_e32 v5, v1
	v_mov_b32_e32 v6, v1
	v_mov_b32_e32 v7, v1
	v_mov_b32_e32 v8, v1
	v_mov_b32_e32 v9, v1
	v_mov_b32_e32 v10, v1
	v_mov_b32_e32 v11, v1
	v_mov_b32_e32 v12, v1
	v_mov_b32_e32 v13, v1
	v_mov_b64_e32 v[94:95], v[14:15]
	v_cmp_gt_u32_e64 s[74:75], 32, v144
	v_lshl_add_u32 v73, v149, 2, s77
	v_lshl_add_u32 v74, v146, 2, s77
	v_add_u32_e32 v75, s19, v166
	v_mov_b32_e32 v16, v1
	v_mov_b32_e32 v17, v1
	v_mov_b32_e32 v18, v1
	v_mov_b32_e32 v19, v1
	v_mov_b32_e32 v20, v1
	v_mov_b32_e32 v21, v1
	v_mov_b32_e32 v22, v1
	v_mov_b32_e32 v23, v1
	v_mov_b32_e32 v24, v1
	v_mov_b32_e32 v25, v1
	v_mov_b32_e32 v26, v1
	v_mov_b32_e32 v27, v1
	v_mov_b32_e32 v28, v1
	v_mov_b32_e32 v29, v1
	v_mov_b32_e32 v30, v1
	v_mov_b32_e32 v31, v1
	v_mov_b32_e32 v32, v1
	v_mov_b32_e32 v33, v1
	v_mov_b32_e32 v34, v1
	v_mov_b32_e32 v35, v1
	v_mov_b32_e32 v36, v1
	v_mov_b32_e32 v37, v1
	v_mov_b32_e32 v38, v1
	v_mov_b32_e32 v39, v1
	v_mov_b32_e32 v40, v1
	v_mov_b32_e32 v41, v1
	v_mov_b32_e32 v42, v1
	v_mov_b32_e32 v43, v1
	v_mov_b32_e32 v44, v1
	v_mov_b32_e32 v45, v1
	v_mov_b32_e32 v46, v1
	v_mov_b32_e32 v47, v1
	s_mov_b32 s36, 0
	v_mov_b32_e32 v172, 0xff800000
	v_mov_b64_e32 v[92:93], v[12:13]
	v_mov_b64_e32 v[90:91], v[10:11]
	v_mov_b64_e32 v[88:89], v[8:9]
	v_mov_b64_e32 v[86:87], v[6:7]
	v_mov_b64_e32 v[84:85], v[4:5]
	v_mov_b64_e32 v[82:83], v[2:3]
	v_mov_b64_e32 v[80:81], v[0:1]
